# layer-1 norm1 row loop software-pipelined (all 12 loads of the next row issued before reducing the current row)
# baseline (speedup 1.0000x reference)
.LBB0_386:
	v_lshl_add_u64 v[196:197], s[6:7], 0, v[80:81]
	v_lshl_add_u64 v[188:189], s[76:77], 0, v[80:81]
	v_add_co_u32_e32 v100, vcc, 0xec800000, v98
	s_nop 1
	v_addc_co_u32_e32 v101, vcc, -1, v99, vcc
	v_add_co_u32_e32 v102, vcc, s60, v98
	s_nop 1
	v_addc_co_u32_e32 v103, vcc, -1, v99, vcc
	global_load_dwordx4 v[64:67], v[196:197], off nt
	global_load_dwordx4 v[68:71], v[196:197], off offset:1024 nt
	global_load_dwordx4 v[72:75], v[196:197], off offset:2048 nt
	global_load_dwordx4 v[76:79], v[196:197], off offset:3072 nt
	global_load_dwordx2 v[140:141], v[98:99], off nt
	global_load_dwordx2 v[142:143], v[98:99], off offset:512 nt
	global_load_dwordx2 v[144:145], v[98:99], off offset:1024 nt
	global_load_dwordx2 v[146:147], v[98:99], off offset:1536 nt
	global_load_dwordx2 v[148:149], v[100:101], off nt
	global_load_dwordx2 v[150:151], v[102:103], off offset:-3584 nt
	global_load_dwordx2 v[152:153], v[102:103], off offset:-3072 nt
	global_load_dwordx2 v[154:155], v[102:103], off offset:-2560 nt
	v_add_u32_e32 v111, 32, v111
	v_cmp_ge_i32_e32 vcc, v111, v104
	s_or_b64 s[16:17], vcc, s[16:17]
	v_lshl_add_u64 v[98:99], v[98:99], 0, s[14:15]
	v_lshl_add_u64 v[80:81], v[80:81], 0, s[12:13]
	s_cmp_eq_u64 s[16:17], 0
	s_cbranch_scc0 .Lpn2_nf
	v_lshl_add_u64 v[196:197], s[6:7], 0, v[80:81]
	v_lshl_add_u64 v[194:195], s[76:77], 0, v[80:81]
	v_add_co_u32_e32 v190, vcc, 0xec800000, v98
	s_nop 1
	v_addc_co_u32_e32 v191, vcc, -1, v99, vcc
	v_add_co_u32_e32 v192, vcc, s60, v98
	s_nop 1
	v_addc_co_u32_e32 v193, vcc, -1, v99, vcc
	global_load_dwordx4 v[156:159], v[196:197], off nt
	global_load_dwordx4 v[160:163], v[196:197], off offset:1024 nt
	global_load_dwordx4 v[164:167], v[196:197], off offset:2048 nt
	global_load_dwordx4 v[168:171], v[196:197], off offset:3072 nt
	global_load_dwordx2 v[172:173], v[98:99], off nt
	global_load_dwordx2 v[174:175], v[98:99], off offset:512 nt
	global_load_dwordx2 v[176:177], v[98:99], off offset:1024 nt
	global_load_dwordx2 v[178:179], v[98:99], off offset:1536 nt
	global_load_dwordx2 v[180:181], v[190:191], off nt
	global_load_dwordx2 v[182:183], v[192:193], off offset:-3584 nt
	global_load_dwordx2 v[184:185], v[192:193], off offset:-3072 nt
	global_load_dwordx2 v[186:187], v[192:193], off offset:-2560 nt
	s_waitcnt vmcnt(12)
	s_branch .Lpn2_ga

.Lpn2_ga:
	v_lshlrev_b32_e32 v120, 16, v140
	v_and_b32_e32 v121, 0xffff0000, v140
	v_lshlrev_b32_e32 v122, 16, v141
	v_and_b32_e32 v123, 0xffff0000, v141
	v_pk_fma_f32 v[64:65], v[60:61], v[120:121], v[64:65]
	v_pk_fma_f32 v[66:67], v[62:63], v[122:123], v[66:67]
	v_lshlrev_b32_e32 v120, 16, v142
	v_and_b32_e32 v121, 0xffff0000, v142
	v_lshlrev_b32_e32 v122, 16, v143
	v_and_b32_e32 v123, 0xffff0000, v143
	v_pk_fma_f32 v[68:69], v[52:53], v[120:121], v[68:69]
	v_pk_fma_f32 v[70:71], v[54:55], v[122:123], v[70:71]
	v_lshlrev_b32_e32 v120, 16, v144
	v_and_b32_e32 v121, 0xffff0000, v144
	v_lshlrev_b32_e32 v122, 16, v145
	v_and_b32_e32 v123, 0xffff0000, v145
	v_pk_fma_f32 v[72:73], v[36:37], v[120:121], v[72:73]
	v_pk_fma_f32 v[74:75], v[38:39], v[122:123], v[74:75]
	v_lshlrev_b32_e32 v120, 16, v146
	v_and_b32_e32 v121, 0xffff0000, v146
	v_lshlrev_b32_e32 v122, 16, v147
	v_and_b32_e32 v123, 0xffff0000, v147
	v_pk_fma_f32 v[76:77], v[32:33], v[120:121], v[76:77]
	v_pk_fma_f32 v[78:79], v[34:35], v[122:123], v[78:79]
	v_lshlrev_b32_e32 v120, 16, v148
	v_and_b32_e32 v121, 0xffff0000, v148
	v_lshlrev_b32_e32 v122, 16, v149
	v_and_b32_e32 v123, 0xffff0000, v149
	v_pk_fma_f32 v[64:65], v[56:57], v[120:121], v[64:65]
	v_pk_fma_f32 v[66:67], v[58:59], v[122:123], v[66:67]
	v_lshlrev_b32_e32 v120, 16, v150
	v_and_b32_e32 v121, 0xffff0000, v150
	v_lshlrev_b32_e32 v122, 16, v151
	v_and_b32_e32 v123, 0xffff0000, v151
	v_pk_fma_f32 v[68:69], v[44:45], v[120:121], v[68:69]
	v_pk_fma_f32 v[70:71], v[46:47], v[122:123], v[70:71]
	v_lshlrev_b32_e32 v120, 16, v152
	v_and_b32_e32 v121, 0xffff0000, v152
	v_lshlrev_b32_e32 v122, 16, v153
	v_and_b32_e32 v123, 0xffff0000, v153
	v_pk_fma_f32 v[72:73], v[40:41], v[120:121], v[72:73]
	v_pk_fma_f32 v[74:75], v[42:43], v[122:123], v[74:75]
	v_lshlrev_b32_e32 v120, 16, v154
	v_and_b32_e32 v121, 0xffff0000, v154
	v_lshlrev_b32_e32 v122, 16, v155
	v_and_b32_e32 v123, 0xffff0000, v155
	v_pk_fma_f32 v[76:77], v[48:49], v[120:121], v[76:77]
	v_pk_fma_f32 v[78:79], v[50:51], v[122:123], v[78:79]
	v_mov_b32_e32 v116, v69
	v_mul_f32_e32 v118, v75, v75
	v_pk_fma_f32 v[118:119], v[74:75], v[74:75], v[118:119] op_sel_hi:[1,1,0]
	v_mov_b32_e32 v114, v65
	v_mov_b32_e32 v115, v67
	v_mov_b32_e32 v112, v64
	v_mov_b32_e32 v113, v66
	v_pk_mul_f32 v[114:115], v[114:115], v[114:115]
	v_mov_b32_e32 v117, v71
	v_pk_fma_f32 v[112:113], v[112:113], v[112:113], v[114:115]
	v_mov_b32_e32 v114, v68
	v_mov_b32_e32 v115, v70
	v_pk_mul_f32 v[116:117], v[116:117], v[116:117]
	v_pk_add_f32 v[112:113], v[112:113], v[112:113] op_sel:[0,1] op_sel_hi:[1,0]
	v_pk_fma_f32 v[114:115], v[114:115], v[114:115], v[116:117]
	v_mul_f32_e32 v116, v73, v73
	v_pk_add_f32 v[114:115], v[114:115], v[114:115] op_sel:[0,1] op_sel_hi:[1,0]
	v_pk_fma_f32 v[116:117], v[72:73], v[72:73], v[116:117] op_sel_hi:[1,1,0]
	v_pk_mul_f32 v[120:121], v[76:77], v[76:77]
	v_pk_mul_f32 v[122:123], v[78:79], v[78:79]
	v_mov_b32_e32 v113, v120
	v_mov_b32_e32 v115, v121
	v_mov_b32_e32 v117, v122
	v_mov_b32_e32 v119, v123
	v_pk_add_f32 v[112:113], v[112:113], v[114:115]
	v_pk_add_f32 v[114:115], v[116:117], v[118:119]
	s_nop 0
	v_pk_add_f32 v[112:113], v[112:113], v[114:115]
	s_nop 0
	v_add_f32_e32 v112, v112, v113
	ds_bpermute_b32 v113, v105, v112
	s_waitcnt lgkmcnt(0)
	v_add_f32_e32 v112, v112, v113
	ds_bpermute_b32 v113, v106, v112
	s_waitcnt lgkmcnt(0)
	v_add_f32_e32 v112, v112, v113
	ds_bpermute_b32 v113, v107, v112
	s_waitcnt lgkmcnt(0)
	v_add_f32_e32 v112, v112, v113
	ds_bpermute_b32 v113, v108, v112
	s_waitcnt lgkmcnt(0)
	v_add_f32_e32 v112, v112, v113
	ds_bpermute_b32 v113, v109, v112
	s_waitcnt lgkmcnt(0)
	v_add_f32_e32 v112, v112, v113
	ds_bpermute_b32 v113, v110, v112
	s_waitcnt lgkmcnt(0)
	v_add_f32_e32 v112, v112, v113
	v_fmamk_f32 v112, v112, 0x3a800000, v201
	v_cmp_gt_f32_e32 vcc, s20, v112
	v_mul_f32_e32 v113, 0x4b800000, v112
	s_nop 0
	v_cndmask_b32_e32 v112, v112, v113, vcc
	v_rsq_f32_e32 v114, v112
	global_store_dwordx4 v[188:189], v[64:67], off nt
	global_store_dwordx4 v[188:189], v[68:71], off offset:1024 nt
	global_store_dwordx4 v[188:189], v[72:75], off offset:2048 nt
	global_store_dwordx4 v[188:189], v[76:79], off offset:3072 nt
	v_mul_f32_e32 v115, 0x45800000, v114
	v_cndmask_b32_e32 v112, v114, v115, vcc
	v_pk_mul_f32 v[66:67], v[66:67], v[112:113] op_sel_hi:[1,0]
	v_pk_mul_f32 v[64:65], v[64:65], v[112:113] op_sel_hi:[1,0]
	v_pk_mul_f32 v[66:67], v[2:3], v[66:67]
	v_pk_mul_f32 v[64:65], v[0:1], v[64:65]
	v_pk_fma_f32 v[66:67], v[82:83], v[66:67], v[18:19]
	v_pk_fma_f32 v[64:65], v[84:85], v[64:65], v[16:17]
	v_cvt_pk_bf16_f32 v64, v64, v65
	v_cvt_pk_bf16_f32 v65, v66, v67
	global_store_dwordx2 v[100:101], v[64:65], off
	v_pk_mul_f32 v[64:65], v[70:71], v[112:113] op_sel_hi:[1,0]
	v_pk_mul_f32 v[66:67], v[68:69], v[112:113] op_sel_hi:[1,0]
	v_pk_mul_f32 v[64:65], v[6:7], v[64:65]
	v_pk_mul_f32 v[66:67], v[4:5], v[66:67]
	v_pk_fma_f32 v[64:65], v[86:87], v[64:65], v[22:23]
	v_pk_fma_f32 v[66:67], v[88:89], v[66:67], v[20:21]
	v_cvt_pk_bf16_f32 v66, v66, v67
	v_cvt_pk_bf16_f32 v67, v64, v65
	global_store_dwordx2 v[102:103], v[66:67], off offset:-3584
	v_pk_mul_f32 v[64:65], v[74:75], v[112:113] op_sel_hi:[1,0]
	v_pk_mul_f32 v[66:67], v[72:73], v[112:113] op_sel_hi:[1,0]
	v_pk_mul_f32 v[64:65], v[10:11], v[64:65]
	v_pk_mul_f32 v[66:67], v[8:9], v[66:67]
	v_pk_fma_f32 v[64:65], v[90:91], v[64:65], v[26:27]
	v_pk_fma_f32 v[66:67], v[92:93], v[66:67], v[24:25]
	s_nop 0
	v_cvt_pk_bf16_f32 v66, v66, v67
	v_cvt_pk_bf16_f32 v67, v64, v65
	global_store_dwordx2 v[102:103], v[66:67], off offset:-3072
	v_pk_mul_f32 v[64:65], v[78:79], v[112:113] op_sel_hi:[1,0]
	v_pk_mul_f32 v[66:67], v[76:77], v[112:113] op_sel_hi:[1,0]
	v_pk_mul_f32 v[64:65], v[14:15], v[64:65]
	v_pk_mul_f32 v[66:67], v[12:13], v[66:67]
	v_pk_fma_f32 v[64:65], v[94:95], v[64:65], v[30:31]
	v_pk_fma_f32 v[66:67], v[96:97], v[66:67], v[28:29]
	s_nop 0
	v_cvt_pk_bf16_f32 v66, v66, v67
	v_cvt_pk_bf16_f32 v67, v64, v65
	global_store_dwordx2 v[102:103], v[66:67], off offset:-2560
	s_cmp_eq_u64 s[16:17], 0
	s_cbranch_scc0 .Lpn2_done
	v_add_u32_e32 v111, 32, v111
	v_cmp_ge_i32_e32 vcc, v111, v104
	s_or_b64 s[16:17], vcc, s[16:17]
	v_lshl_add_u64 v[98:99], v[98:99], 0, s[14:15]
	v_lshl_add_u64 v[80:81], v[80:81], 0, s[12:13]
	s_cmp_eq_u64 s[16:17], 0
	s_cbranch_scc0 .Lpn2_nb
	v_lshl_add_u64 v[196:197], s[6:7], 0, v[80:81]
	v_lshl_add_u64 v[188:189], s[76:77], 0, v[80:81]
	v_add_co_u32_e32 v100, vcc, 0xec800000, v98
	s_nop 1
	v_addc_co_u32_e32 v101, vcc, -1, v99, vcc
	v_add_co_u32_e32 v102, vcc, s60, v98
	s_nop 1
	v_addc_co_u32_e32 v103, vcc, -1, v99, vcc
	global_load_dwordx4 v[64:67], v[196:197], off nt
	global_load_dwordx4 v[68:71], v[196:197], off offset:1024 nt
	global_load_dwordx4 v[72:75], v[196:197], off offset:2048 nt
	global_load_dwordx4 v[76:79], v[196:197], off offset:3072 nt
	global_load_dwordx2 v[140:141], v[98:99], off nt
	global_load_dwordx2 v[142:143], v[98:99], off offset:512 nt
	global_load_dwordx2 v[144:145], v[98:99], off offset:1024 nt
	global_load_dwordx2 v[146:147], v[98:99], off offset:1536 nt
	global_load_dwordx2 v[148:149], v[100:101], off nt
	global_load_dwordx2 v[150:151], v[102:103], off offset:-3584 nt
	global_load_dwordx2 v[152:153], v[102:103], off offset:-3072 nt
	global_load_dwordx2 v[154:155], v[102:103], off offset:-2560 nt
	s_waitcnt vmcnt(20)
	s_branch .Lpn2_gb

.Lpn2_gb:
	v_lshlrev_b32_e32 v120, 16, v172
	v_and_b32_e32 v121, 0xffff0000, v172
	v_lshlrev_b32_e32 v122, 16, v173
	v_and_b32_e32 v123, 0xffff0000, v173
	v_pk_fma_f32 v[156:157], v[60:61], v[120:121], v[156:157]
	v_pk_fma_f32 v[158:159], v[62:63], v[122:123], v[158:159]
	v_lshlrev_b32_e32 v120, 16, v174
	v_and_b32_e32 v121, 0xffff0000, v174
	v_lshlrev_b32_e32 v122, 16, v175
	v_and_b32_e32 v123, 0xffff0000, v175
	v_pk_fma_f32 v[160:161], v[52:53], v[120:121], v[160:161]
	v_pk_fma_f32 v[162:163], v[54:55], v[122:123], v[162:163]
	v_lshlrev_b32_e32 v120, 16, v176
	v_and_b32_e32 v121, 0xffff0000, v176
	v_lshlrev_b32_e32 v122, 16, v177
	v_and_b32_e32 v123, 0xffff0000, v177
	v_pk_fma_f32 v[164:165], v[36:37], v[120:121], v[164:165]
	v_pk_fma_f32 v[166:167], v[38:39], v[122:123], v[166:167]
	v_lshlrev_b32_e32 v120, 16, v178
	v_and_b32_e32 v121, 0xffff0000, v178
	v_lshlrev_b32_e32 v122, 16, v179
	v_and_b32_e32 v123, 0xffff0000, v179
	v_pk_fma_f32 v[168:169], v[32:33], v[120:121], v[168:169]
	v_pk_fma_f32 v[170:171], v[34:35], v[122:123], v[170:171]
	v_lshlrev_b32_e32 v120, 16, v180
	v_and_b32_e32 v121, 0xffff0000, v180
	v_lshlrev_b32_e32 v122, 16, v181
	v_and_b32_e32 v123, 0xffff0000, v181
	v_pk_fma_f32 v[156:157], v[56:57], v[120:121], v[156:157]
	v_pk_fma_f32 v[158:159], v[58:59], v[122:123], v[158:159]
	v_lshlrev_b32_e32 v120, 16, v182
	v_and_b32_e32 v121, 0xffff0000, v182
	v_lshlrev_b32_e32 v122, 16, v183
	v_and_b32_e32 v123, 0xffff0000, v183
	v_pk_fma_f32 v[160:161], v[44:45], v[120:121], v[160:161]
	v_pk_fma_f32 v[162:163], v[46:47], v[122:123], v[162:163]
	v_lshlrev_b32_e32 v120, 16, v184
	v_and_b32_e32 v121, 0xffff0000, v184
	v_lshlrev_b32_e32 v122, 16, v185
	v_and_b32_e32 v123, 0xffff0000, v185
	v_pk_fma_f32 v[164:165], v[40:41], v[120:121], v[164:165]
	v_pk_fma_f32 v[166:167], v[42:43], v[122:123], v[166:167]
	v_lshlrev_b32_e32 v120, 16, v186
	v_and_b32_e32 v121, 0xffff0000, v186
	v_lshlrev_b32_e32 v122, 16, v187
	v_and_b32_e32 v123, 0xffff0000, v187
	v_pk_fma_f32 v[168:169], v[48:49], v[120:121], v[168:169]
	v_pk_fma_f32 v[170:171], v[50:51], v[122:123], v[170:171]
	v_mov_b32_e32 v116, v161
	v_mul_f32_e32 v118, v167, v167
	v_pk_fma_f32 v[118:119], v[166:167], v[166:167], v[118:119] op_sel_hi:[1,1,0]
	v_mov_b32_e32 v114, v157
	v_mov_b32_e32 v115, v159
	v_mov_b32_e32 v112, v156
	v_mov_b32_e32 v113, v158
	v_pk_mul_f32 v[114:115], v[114:115], v[114:115]
	v_mov_b32_e32 v117, v163
	v_pk_fma_f32 v[112:113], v[112:113], v[112:113], v[114:115]
	v_mov_b32_e32 v114, v160
	v_mov_b32_e32 v115, v162
	v_pk_mul_f32 v[116:117], v[116:117], v[116:117]
	v_pk_add_f32 v[112:113], v[112:113], v[112:113] op_sel:[0,1] op_sel_hi:[1,0]
	v_pk_fma_f32 v[114:115], v[114:115], v[114:115], v[116:117]
	v_mul_f32_e32 v116, v165, v165
	v_pk_add_f32 v[114:115], v[114:115], v[114:115] op_sel:[0,1] op_sel_hi:[1,0]
	v_pk_fma_f32 v[116:117], v[164:165], v[164:165], v[116:117] op_sel_hi:[1,1,0]
	v_pk_mul_f32 v[120:121], v[168:169], v[168:169]
	v_pk_mul_f32 v[122:123], v[170:171], v[170:171]
	v_mov_b32_e32 v113, v120
	v_mov_b32_e32 v115, v121
	v_mov_b32_e32 v117, v122
	v_mov_b32_e32 v119, v123
	v_pk_add_f32 v[112:113], v[112:113], v[114:115]
	v_pk_add_f32 v[114:115], v[116:117], v[118:119]
	s_nop 0
	v_pk_add_f32 v[112:113], v[112:113], v[114:115]
	s_nop 0
	v_add_f32_e32 v112, v112, v113
	ds_bpermute_b32 v113, v105, v112
	s_waitcnt lgkmcnt(0)
	v_add_f32_e32 v112, v112, v113
	ds_bpermute_b32 v113, v106, v112
	s_waitcnt lgkmcnt(0)
	v_add_f32_e32 v112, v112, v113
	ds_bpermute_b32 v113, v107, v112
	s_waitcnt lgkmcnt(0)
	v_add_f32_e32 v112, v112, v113
	ds_bpermute_b32 v113, v108, v112
	s_waitcnt lgkmcnt(0)
	v_add_f32_e32 v112, v112, v113
	ds_bpermute_b32 v113, v109, v112
	s_waitcnt lgkmcnt(0)
	v_add_f32_e32 v112, v112, v113
	ds_bpermute_b32 v113, v110, v112
	s_waitcnt lgkmcnt(0)
	v_add_f32_e32 v112, v112, v113
	v_fmamk_f32 v112, v112, 0x3a800000, v201
	v_cmp_gt_f32_e32 vcc, s20, v112
	v_mul_f32_e32 v113, 0x4b800000, v112
	s_nop 0
	v_cndmask_b32_e32 v112, v112, v113, vcc
	v_rsq_f32_e32 v114, v112
	global_store_dwordx4 v[194:195], v[156:159], off nt
	global_store_dwordx4 v[194:195], v[160:163], off offset:1024 nt
	global_store_dwordx4 v[194:195], v[164:167], off offset:2048 nt
	global_store_dwordx4 v[194:195], v[168:171], off offset:3072 nt
	v_mul_f32_e32 v115, 0x45800000, v114
	v_cndmask_b32_e32 v112, v114, v115, vcc
	v_pk_mul_f32 v[158:159], v[158:159], v[112:113] op_sel_hi:[1,0]
	v_pk_mul_f32 v[156:157], v[156:157], v[112:113] op_sel_hi:[1,0]
	v_pk_mul_f32 v[158:159], v[2:3], v[158:159]
	v_pk_mul_f32 v[156:157], v[0:1], v[156:157]
	v_pk_fma_f32 v[158:159], v[82:83], v[158:159], v[18:19]
	v_pk_fma_f32 v[156:157], v[84:85], v[156:157], v[16:17]
	v_cvt_pk_bf16_f32 v156, v156, v157
	v_cvt_pk_bf16_f32 v157, v158, v159
	global_store_dwordx2 v[190:191], v[156:157], off
	v_pk_mul_f32 v[156:157], v[162:163], v[112:113] op_sel_hi:[1,0]
	v_pk_mul_f32 v[158:159], v[160:161], v[112:113] op_sel_hi:[1,0]
	v_pk_mul_f32 v[156:157], v[6:7], v[156:157]
	v_pk_mul_f32 v[158:159], v[4:5], v[158:159]
	v_pk_fma_f32 v[156:157], v[86:87], v[156:157], v[22:23]
	v_pk_fma_f32 v[158:159], v[88:89], v[158:159], v[20:21]
	v_cvt_pk_bf16_f32 v158, v158, v159
	v_cvt_pk_bf16_f32 v159, v156, v157
	global_store_dwordx2 v[192:193], v[158:159], off offset:-3584
	v_pk_mul_f32 v[156:157], v[166:167], v[112:113] op_sel_hi:[1,0]
	v_pk_mul_f32 v[158:159], v[164:165], v[112:113] op_sel_hi:[1,0]
	v_pk_mul_f32 v[156:157], v[10:11], v[156:157]
	v_pk_mul_f32 v[158:159], v[8:9], v[158:159]
	v_pk_fma_f32 v[156:157], v[90:91], v[156:157], v[26:27]
	v_pk_fma_f32 v[158:159], v[92:93], v[158:159], v[24:25]
	s_nop 0
	v_cvt_pk_bf16_f32 v158, v158, v159
	v_cvt_pk_bf16_f32 v159, v156, v157
	global_store_dwordx2 v[192:193], v[158:159], off offset:-3072
	v_pk_mul_f32 v[156:157], v[170:171], v[112:113] op_sel_hi:[1,0]
	v_pk_mul_f32 v[158:159], v[168:169], v[112:113] op_sel_hi:[1,0]
	v_pk_mul_f32 v[156:157], v[14:15], v[156:157]
	v_pk_mul_f32 v[158:159], v[12:13], v[158:159]
	v_pk_fma_f32 v[156:157], v[94:95], v[156:157], v[30:31]
	v_pk_fma_f32 v[158:159], v[96:97], v[158:159], v[28:29]
	s_nop 0
	v_cvt_pk_bf16_f32 v158, v158, v159
	v_cvt_pk_bf16_f32 v159, v156, v157
	global_store_dwordx2 v[192:193], v[158:159], off offset:-2560
	s_cmp_eq_u64 s[16:17], 0
	s_cbranch_scc0 .Lpn2_done
	v_add_u32_e32 v111, 32, v111
	v_cmp_ge_i32_e32 vcc, v111, v104
	s_or_b64 s[16:17], vcc, s[16:17]
	v_lshl_add_u64 v[98:99], v[98:99], 0, s[14:15]
	v_lshl_add_u64 v[80:81], v[80:81], 0, s[12:13]
	s_cmp_eq_u64 s[16:17], 0
	s_cbranch_scc0 .Lpn2_na
	v_lshl_add_u64 v[196:197], s[6:7], 0, v[80:81]
	v_lshl_add_u64 v[194:195], s[76:77], 0, v[80:81]
	v_add_co_u32_e32 v190, vcc, 0xec800000, v98
	s_nop 1
	v_addc_co_u32_e32 v191, vcc, -1, v99, vcc
	v_add_co_u32_e32 v192, vcc, s60, v98
	s_nop 1
	v_addc_co_u32_e32 v193, vcc, -1, v99, vcc
	global_load_dwordx4 v[156:159], v[196:197], off nt
	global_load_dwordx4 v[160:163], v[196:197], off offset:1024 nt
	global_load_dwordx4 v[164:167], v[196:197], off offset:2048 nt
	global_load_dwordx4 v[168:171], v[196:197], off offset:3072 nt
	global_load_dwordx2 v[172:173], v[98:99], off nt
	global_load_dwordx2 v[174:175], v[98:99], off offset:512 nt
	global_load_dwordx2 v[176:177], v[98:99], off offset:1024 nt
	global_load_dwordx2 v[178:179], v[98:99], off offset:1536 nt
	global_load_dwordx2 v[180:181], v[190:191], off nt
	global_load_dwordx2 v[182:183], v[192:193], off offset:-3584 nt
	global_load_dwordx2 v[184:185], v[192:193], off offset:-3072 nt
	global_load_dwordx2 v[186:187], v[192:193], off offset:-2560 nt
	s_waitcnt vmcnt(20)
	s_branch .Lpn2_ga
.Lpn2_na:
	s_waitcnt vmcnt(8)
	s_branch .Lpn2_ga
.Lpn2_done:
	s_or_b64 exec, exec, s[16:17]
	s_cmp_lg_u32 s100, 0
	s_cbranch_scc1 .Lnt_done_n2
	s_mov_b32 s100, 1
	s_mov_b64 s[16:17], 0
	v_add_u32_e32 v111, 0x700, v111
	v_add_u32_e32 v104, 0x800, v104
	s_mov_b32 vcc_lo, 0x380000
	s_mov_b32 vcc_hi, 0
	v_lshl_add_u64 v[98:99], v[98:99], 0, vcc
	s_mov_b32 vcc_lo, 0x700000
	v_lshl_add_u64 v[80:81], v[80:81], 0, vcc
	s_branch .LBB0_386
